# P0: dot16x2 rewritten with packed FMAs (368 vs 734 instr per 2 rows)
# speedup vs baseline: 1.2315x; 1.0058x over previous
.LBB0_38:
	s_add_i32 s25, s16, s78
	s_cmp_lt_i32 s25, 0xc000
	s_cselect_b32 s14, s25, s16
	s_add_i32 s10, s16, 0xffff8000
	s_ashr_i32 s17, s16, 31
	s_cmp_lt_i32 s16, 0x8000
	v_readlane_b32 s36, v253, 0
	s_cselect_b32 s11, s17, 0
	s_cselect_b32 s10, s16, s10
	v_readlane_b32 s37, v253, 1
	v_readlane_b32 s38, v253, 2
	v_readlane_b32 s39, v253, 3
	s_cselect_b32 s15, s37, s39
	s_cselect_b32 s18, s36, s38
	s_lshl_b64 s[10:11], s[10:11], 12
	s_add_u32 s10, s18, s10
	s_addc_u32 s11, s15, s11
	s_waitcnt lgkmcnt(0)
	v_lshl_add_u64 v[2:3], s[10:11], 0, v[42:43]
	s_add_i32 s10, s14, 0xffff8000
	s_ashr_i32 s15, s14, 31
	s_cmp_lt_i32 s14, 0x8000
	s_cselect_b32 s11, s15, 0
	s_cselect_b32 s10, s14, s10
	s_cselect_b32 s18, s37, s39
	s_cselect_b32 s19, s36, s38
	s_lshl_b64 s[10:11], s[10:11], 12
	s_add_u32 s10, s19, s10
	global_load_dwordx4 v[26:29], v[2:3], off
	global_load_dwordx4 v[22:25], v[2:3], off offset:1024
	s_addc_u32 s11, s18, s11
	global_load_dwordx4 v[10:13], v[2:3], off offset:2048
	v_lshl_add_u64 v[6:7], s[10:11], 0, v[42:43]
	global_load_dwordx4 v[2:5], v[2:3], off offset:3072
	s_nop 0
	global_load_dwordx4 v[30:33], v[6:7], off
	global_load_dwordx4 v[18:21], v[6:7], off offset:1024
	global_load_dwordx4 v[14:17], v[6:7], off offset:2048
	s_nop 0
	global_load_dwordx4 v[6:9], v[6:7], off offset:3072
	s_lshl_b64 s[10:11], s[16:17], 11
	s_lshl_b64 s[18:19], s[14:15], 11
	v_lshl_add_u64 v[34:35], v[40:41], 0, s[10:11]
	v_lshl_add_u64 v[36:37], v[40:41], 0, s[18:19]
	v_readlane_b32 s40, v253, 4
	v_readlane_b32 s41, v253, 5
	v_readlane_b32 s42, v253, 6
	v_readlane_b32 s43, v253, 7
	v_readlane_b32 s44, v253, 8
	v_readlane_b32 s45, v253, 9
	v_readlane_b32 s46, v253, 10
	v_readlane_b32 s47, v253, 11
	v_readlane_b32 s48, v253, 12
	v_readlane_b32 s49, v253, 13
	v_readlane_b32 s50, v253, 14
	v_readlane_b32 s51, v253, 15
	s_waitcnt vmcnt(7)
	v_cvt_pk_bf16_f32 v56, v26, v27
	v_cvt_pk_bf16_f32 v57, v28, v29
	s_waitcnt vmcnt(6)
	v_cvt_pk_bf16_f32 v58, v22, v23
	v_cvt_pk_bf16_f32 v59, v24, v25
	s_waitcnt vmcnt(5)
	v_cvt_pk_bf16_f32 v60, v10, v11
	v_cvt_pk_bf16_f32 v61, v12, v13
	s_waitcnt vmcnt(4)
	v_cvt_pk_bf16_f32 v62, v2, v3
	v_cvt_pk_bf16_f32 v63, v4, v5
	global_store_dwordx2 v[34:35], v[56:57], off
	global_store_dwordx2 v[34:35], v[58:59], off offset:512
	global_store_dwordx2 v[34:35], v[60:61], off offset:1024
	global_store_dwordx2 v[34:35], v[62:63], off offset:1536
	s_waitcnt vmcnt(7)
	v_cvt_pk_bf16_f32 v34, v30, v31
	v_cvt_pk_bf16_f32 v35, v32, v33
	s_waitcnt vmcnt(6)
	v_cvt_pk_bf16_f32 v56, v18, v19
	v_cvt_pk_bf16_f32 v57, v20, v21
	s_waitcnt vmcnt(5)
	v_cvt_pk_bf16_f32 v58, v14, v15
	v_cvt_pk_bf16_f32 v59, v16, v17
	s_waitcnt vmcnt(4)
	v_cvt_pk_bf16_f32 v60, v6, v7
	v_cvt_pk_bf16_f32 v61, v8, v9
	global_store_dwordx2 v[36:37], v[34:35], off
	global_store_dwordx2 v[36:37], v[56:57], off offset:512
	global_store_dwordx2 v[36:37], v[58:59], off offset:1024
	global_store_dwordx2 v[36:37], v[60:61], off offset:1536
	ds_read_b128 v[176:179], v44 offset:0
	ds_read_b128 v[180:183], v44 offset:1024
	ds_read_b128 v[184:187], v44 offset:2048
	ds_read_b128 v[188:191], v44 offset:3072
	ds_read_b128 v[192:195], v44 offset:4096
	ds_read_b128 v[196:199], v44 offset:5120
	ds_read_b128 v[200:203], v44 offset:6144
	ds_read_b128 v[204:207], v44 offset:7168
	s_waitcnt lgkmcnt(4)
	v_pk_mul_f32 v[208:209], v[26:27], v[176:177]
	v_pk_mul_f32 v[210:211], v[30:31], v[176:177]
	v_pk_fma_f32 v[208:209], v[28:29], v[178:179], v[208:209]
	v_pk_fma_f32 v[210:211], v[32:33], v[178:179], v[210:211]
	v_pk_fma_f32 v[208:209], v[22:23], v[180:181], v[208:209]
	v_pk_fma_f32 v[210:211], v[18:19], v[180:181], v[210:211]
	v_pk_fma_f32 v[208:209], v[24:25], v[182:183], v[208:209]
	v_pk_fma_f32 v[210:211], v[20:21], v[182:183], v[210:211]
	v_pk_fma_f32 v[208:209], v[10:11], v[184:185], v[208:209]
	v_pk_fma_f32 v[210:211], v[14:15], v[184:185], v[210:211]
	v_pk_fma_f32 v[208:209], v[12:13], v[186:187], v[208:209]
	v_pk_fma_f32 v[210:211], v[16:17], v[186:187], v[210:211]
	v_pk_fma_f32 v[208:209], v[2:3], v[188:189], v[208:209]
	v_pk_fma_f32 v[210:211], v[6:7], v[188:189], v[210:211]
	v_pk_fma_f32 v[208:209], v[4:5], v[190:191], v[208:209]
	v_pk_fma_f32 v[210:211], v[8:9], v[190:191], v[210:211]
	v_add_f32_e32 v142, v208, v209
	v_add_f32_e32 v143, v210, v211
	ds_read_b128 v[176:179], v44 offset:8192
	ds_read_b128 v[180:183], v44 offset:9216
	ds_read_b128 v[184:187], v44 offset:10240
	ds_read_b128 v[188:191], v44 offset:11264
	s_waitcnt lgkmcnt(4)
	v_pk_mul_f32 v[208:209], v[26:27], v[192:193]
	v_pk_mul_f32 v[210:211], v[30:31], v[192:193]
	v_pk_fma_f32 v[208:209], v[28:29], v[194:195], v[208:209]
	v_pk_fma_f32 v[210:211], v[32:33], v[194:195], v[210:211]
	v_pk_fma_f32 v[208:209], v[22:23], v[196:197], v[208:209]
	v_pk_fma_f32 v[210:211], v[18:19], v[196:197], v[210:211]
	v_pk_fma_f32 v[208:209], v[24:25], v[198:199], v[208:209]
	v_pk_fma_f32 v[210:211], v[20:21], v[198:199], v[210:211]
	v_pk_fma_f32 v[208:209], v[10:11], v[200:201], v[208:209]
	v_pk_fma_f32 v[210:211], v[14:15], v[200:201], v[210:211]
	v_pk_fma_f32 v[208:209], v[12:13], v[202:203], v[208:209]
	v_pk_fma_f32 v[210:211], v[16:17], v[202:203], v[210:211]
	v_pk_fma_f32 v[208:209], v[2:3], v[204:205], v[208:209]
	v_pk_fma_f32 v[210:211], v[6:7], v[204:205], v[210:211]
	v_pk_fma_f32 v[208:209], v[4:5], v[206:207], v[208:209]
	v_pk_fma_f32 v[210:211], v[8:9], v[206:207], v[210:211]
	v_add_f32_e32 v144, v208, v209
	v_add_f32_e32 v145, v210, v211
	ds_read_b128 v[192:195], v44 offset:12288
	ds_read_b128 v[196:199], v44 offset:13312
	ds_read_b128 v[200:203], v44 offset:14336
	ds_read_b128 v[204:207], v44 offset:15360
	s_waitcnt lgkmcnt(4)
	v_pk_mul_f32 v[208:209], v[26:27], v[176:177]
	v_pk_mul_f32 v[210:211], v[30:31], v[176:177]
	v_pk_fma_f32 v[208:209], v[28:29], v[178:179], v[208:209]
	v_pk_fma_f32 v[210:211], v[32:33], v[178:179], v[210:211]
	v_pk_fma_f32 v[208:209], v[22:23], v[180:181], v[208:209]
	v_pk_fma_f32 v[210:211], v[18:19], v[180:181], v[210:211]
	v_pk_fma_f32 v[208:209], v[24:25], v[182:183], v[208:209]
	v_pk_fma_f32 v[210:211], v[20:21], v[182:183], v[210:211]
	v_pk_fma_f32 v[208:209], v[10:11], v[184:185], v[208:209]
	v_pk_fma_f32 v[210:211], v[14:15], v[184:185], v[210:211]
	v_pk_fma_f32 v[208:209], v[12:13], v[186:187], v[208:209]
	v_pk_fma_f32 v[210:211], v[16:17], v[186:187], v[210:211]
	v_pk_fma_f32 v[208:209], v[2:3], v[188:189], v[208:209]
	v_pk_fma_f32 v[210:211], v[6:7], v[188:189], v[210:211]
	v_pk_fma_f32 v[208:209], v[4:5], v[190:191], v[208:209]
	v_pk_fma_f32 v[210:211], v[8:9], v[190:191], v[210:211]
	v_add_f32_e32 v146, v208, v209
	v_add_f32_e32 v147, v210, v211
	ds_read_b128 v[176:179], v44 offset:16384
	ds_read_b128 v[180:183], v44 offset:17408
	ds_read_b128 v[184:187], v44 offset:18432
	ds_read_b128 v[188:191], v44 offset:19456
	s_waitcnt lgkmcnt(4)
	v_pk_mul_f32 v[208:209], v[26:27], v[192:193]
	v_pk_mul_f32 v[210:211], v[30:31], v[192:193]
	v_pk_fma_f32 v[208:209], v[28:29], v[194:195], v[208:209]
	v_pk_fma_f32 v[210:211], v[32:33], v[194:195], v[210:211]
	v_pk_fma_f32 v[208:209], v[22:23], v[196:197], v[208:209]
	v_pk_fma_f32 v[210:211], v[18:19], v[196:197], v[210:211]
	v_pk_fma_f32 v[208:209], v[24:25], v[198:199], v[208:209]
	v_pk_fma_f32 v[210:211], v[20:21], v[198:199], v[210:211]
	v_pk_fma_f32 v[208:209], v[10:11], v[200:201], v[208:209]
	v_pk_fma_f32 v[210:211], v[14:15], v[200:201], v[210:211]
	v_pk_fma_f32 v[208:209], v[12:13], v[202:203], v[208:209]
	v_pk_fma_f32 v[210:211], v[16:17], v[202:203], v[210:211]
	v_pk_fma_f32 v[208:209], v[2:3], v[204:205], v[208:209]
	v_pk_fma_f32 v[210:211], v[6:7], v[204:205], v[210:211]
	v_pk_fma_f32 v[208:209], v[4:5], v[206:207], v[208:209]
	v_pk_fma_f32 v[210:211], v[8:9], v[206:207], v[210:211]
	v_add_f32_e32 v148, v208, v209
	v_add_f32_e32 v149, v210, v211
	ds_read_b128 v[192:195], v44 offset:20480
	ds_read_b128 v[196:199], v44 offset:21504
	ds_read_b128 v[200:203], v44 offset:22528
	ds_read_b128 v[204:207], v44 offset:23552
	s_waitcnt lgkmcnt(4)
	v_pk_mul_f32 v[208:209], v[26:27], v[176:177]
	v_pk_mul_f32 v[210:211], v[30:31], v[176:177]
	v_pk_fma_f32 v[208:209], v[28:29], v[178:179], v[208:209]
	v_pk_fma_f32 v[210:211], v[32:33], v[178:179], v[210:211]
	v_pk_fma_f32 v[208:209], v[22:23], v[180:181], v[208:209]
	v_pk_fma_f32 v[210:211], v[18:19], v[180:181], v[210:211]
	v_pk_fma_f32 v[208:209], v[24:25], v[182:183], v[208:209]
	v_pk_fma_f32 v[210:211], v[20:21], v[182:183], v[210:211]
	v_pk_fma_f32 v[208:209], v[10:11], v[184:185], v[208:209]
	v_pk_fma_f32 v[210:211], v[14:15], v[184:185], v[210:211]
	v_pk_fma_f32 v[208:209], v[12:13], v[186:187], v[208:209]
	v_pk_fma_f32 v[210:211], v[16:17], v[186:187], v[210:211]
	v_pk_fma_f32 v[208:209], v[2:3], v[188:189], v[208:209]
	v_pk_fma_f32 v[210:211], v[6:7], v[188:189], v[210:211]
	v_pk_fma_f32 v[208:209], v[4:5], v[190:191], v[208:209]
	v_pk_fma_f32 v[210:211], v[8:9], v[190:191], v[210:211]
	v_add_f32_e32 v150, v208, v209
	v_add_f32_e32 v151, v210, v211
	ds_read_b128 v[176:179], v44 offset:24576
	ds_read_b128 v[180:183], v44 offset:25600
	ds_read_b128 v[184:187], v44 offset:26624
	ds_read_b128 v[188:191], v44 offset:27648
	s_waitcnt lgkmcnt(4)
	v_pk_mul_f32 v[208:209], v[26:27], v[192:193]
	v_pk_mul_f32 v[210:211], v[30:31], v[192:193]
	v_pk_fma_f32 v[208:209], v[28:29], v[194:195], v[208:209]
	v_pk_fma_f32 v[210:211], v[32:33], v[194:195], v[210:211]
	v_pk_fma_f32 v[208:209], v[22:23], v[196:197], v[208:209]
	v_pk_fma_f32 v[210:211], v[18:19], v[196:197], v[210:211]
	v_pk_fma_f32 v[208:209], v[24:25], v[198:199], v[208:209]
	v_pk_fma_f32 v[210:211], v[20:21], v[198:199], v[210:211]
	v_pk_fma_f32 v[208:209], v[10:11], v[200:201], v[208:209]
	v_pk_fma_f32 v[210:211], v[14:15], v[200:201], v[210:211]
	v_pk_fma_f32 v[208:209], v[12:13], v[202:203], v[208:209]
	v_pk_fma_f32 v[210:211], v[16:17], v[202:203], v[210:211]
	v_pk_fma_f32 v[208:209], v[2:3], v[204:205], v[208:209]
	v_pk_fma_f32 v[210:211], v[6:7], v[204:205], v[210:211]
	v_pk_fma_f32 v[208:209], v[4:5], v[206:207], v[208:209]
	v_pk_fma_f32 v[210:211], v[8:9], v[206:207], v[210:211]
	v_add_f32_e32 v152, v208, v209
	v_add_f32_e32 v153, v210, v211
	ds_read_b128 v[192:195], v44 offset:28672
	ds_read_b128 v[196:199], v44 offset:29696
	ds_read_b128 v[200:203], v44 offset:30720
	ds_read_b128 v[204:207], v44 offset:31744
	s_waitcnt lgkmcnt(4)
	v_pk_mul_f32 v[208:209], v[26:27], v[176:177]
	v_pk_mul_f32 v[210:211], v[30:31], v[176:177]
	v_pk_fma_f32 v[208:209], v[28:29], v[178:179], v[208:209]
	v_pk_fma_f32 v[210:211], v[32:33], v[178:179], v[210:211]
	v_pk_fma_f32 v[208:209], v[22:23], v[180:181], v[208:209]
	v_pk_fma_f32 v[210:211], v[18:19], v[180:181], v[210:211]
	v_pk_fma_f32 v[208:209], v[24:25], v[182:183], v[208:209]
	v_pk_fma_f32 v[210:211], v[20:21], v[182:183], v[210:211]
	v_pk_fma_f32 v[208:209], v[10:11], v[184:185], v[208:209]
	v_pk_fma_f32 v[210:211], v[14:15], v[184:185], v[210:211]
	v_pk_fma_f32 v[208:209], v[12:13], v[186:187], v[208:209]
	v_pk_fma_f32 v[210:211], v[16:17], v[186:187], v[210:211]
	v_pk_fma_f32 v[208:209], v[2:3], v[188:189], v[208:209]
	v_pk_fma_f32 v[210:211], v[6:7], v[188:189], v[210:211]
	v_pk_fma_f32 v[208:209], v[4:5], v[190:191], v[208:209]
	v_pk_fma_f32 v[210:211], v[8:9], v[190:191], v[210:211]
	v_add_f32_e32 v154, v208, v209
	v_add_f32_e32 v155, v210, v211
	ds_read_b128 v[176:179], v44 offset:32768
	ds_read_b128 v[180:183], v44 offset:33792
	ds_read_b128 v[184:187], v44 offset:34816
	ds_read_b128 v[188:191], v44 offset:35840
	s_waitcnt lgkmcnt(4)
	v_pk_mul_f32 v[208:209], v[26:27], v[192:193]
	v_pk_mul_f32 v[210:211], v[30:31], v[192:193]
	v_pk_fma_f32 v[208:209], v[28:29], v[194:195], v[208:209]
	v_pk_fma_f32 v[210:211], v[32:33], v[194:195], v[210:211]
	v_pk_fma_f32 v[208:209], v[22:23], v[196:197], v[208:209]
	v_pk_fma_f32 v[210:211], v[18:19], v[196:197], v[210:211]
	v_pk_fma_f32 v[208:209], v[24:25], v[198:199], v[208:209]
	v_pk_fma_f32 v[210:211], v[20:21], v[198:199], v[210:211]
	v_pk_fma_f32 v[208:209], v[10:11], v[200:201], v[208:209]
	v_pk_fma_f32 v[210:211], v[14:15], v[200:201], v[210:211]
	v_pk_fma_f32 v[208:209], v[12:13], v[202:203], v[208:209]
	v_pk_fma_f32 v[210:211], v[16:17], v[202:203], v[210:211]
	v_pk_fma_f32 v[208:209], v[2:3], v[204:205], v[208:209]
	v_pk_fma_f32 v[210:211], v[6:7], v[204:205], v[210:211]
	v_pk_fma_f32 v[208:209], v[4:5], v[206:207], v[208:209]
	v_pk_fma_f32 v[210:211], v[8:9], v[206:207], v[210:211]
	v_add_f32_e32 v156, v208, v209
	v_add_f32_e32 v157, v210, v211
	ds_read_b128 v[192:195], v44 offset:36864
	ds_read_b128 v[196:199], v44 offset:37888
	ds_read_b128 v[200:203], v44 offset:38912
	ds_read_b128 v[204:207], v44 offset:39936
	s_waitcnt lgkmcnt(4)
	v_pk_mul_f32 v[208:209], v[26:27], v[176:177]
	v_pk_mul_f32 v[210:211], v[30:31], v[176:177]
	v_pk_fma_f32 v[208:209], v[28:29], v[178:179], v[208:209]
	v_pk_fma_f32 v[210:211], v[32:33], v[178:179], v[210:211]
	v_pk_fma_f32 v[208:209], v[22:23], v[180:181], v[208:209]
	v_pk_fma_f32 v[210:211], v[18:19], v[180:181], v[210:211]
	v_pk_fma_f32 v[208:209], v[24:25], v[182:183], v[208:209]
	v_pk_fma_f32 v[210:211], v[20:21], v[182:183], v[210:211]
	v_pk_fma_f32 v[208:209], v[10:11], v[184:185], v[208:209]
	v_pk_fma_f32 v[210:211], v[14:15], v[184:185], v[210:211]
	v_pk_fma_f32 v[208:209], v[12:13], v[186:187], v[208:209]
	v_pk_fma_f32 v[210:211], v[16:17], v[186:187], v[210:211]
	v_pk_fma_f32 v[208:209], v[2:3], v[188:189], v[208:209]
	v_pk_fma_f32 v[210:211], v[6:7], v[188:189], v[210:211]
	v_pk_fma_f32 v[208:209], v[4:5], v[190:191], v[208:209]
	v_pk_fma_f32 v[210:211], v[8:9], v[190:191], v[210:211]
	v_add_f32_e32 v158, v208, v209
	v_add_f32_e32 v159, v210, v211
	ds_read_b128 v[176:179], v44 offset:40960
	ds_read_b128 v[180:183], v44 offset:41984
	ds_read_b128 v[184:187], v44 offset:43008
	ds_read_b128 v[188:191], v44 offset:44032
	s_waitcnt lgkmcnt(4)
	v_pk_mul_f32 v[208:209], v[26:27], v[192:193]
	v_pk_mul_f32 v[210:211], v[30:31], v[192:193]
	v_pk_fma_f32 v[208:209], v[28:29], v[194:195], v[208:209]
	v_pk_fma_f32 v[210:211], v[32:33], v[194:195], v[210:211]
	v_pk_fma_f32 v[208:209], v[22:23], v[196:197], v[208:209]
	v_pk_fma_f32 v[210:211], v[18:19], v[196:197], v[210:211]
	v_pk_fma_f32 v[208:209], v[24:25], v[198:199], v[208:209]
	v_pk_fma_f32 v[210:211], v[20:21], v[198:199], v[210:211]
	v_pk_fma_f32 v[208:209], v[10:11], v[200:201], v[208:209]
	v_pk_fma_f32 v[210:211], v[14:15], v[200:201], v[210:211]
	v_pk_fma_f32 v[208:209], v[12:13], v[202:203], v[208:209]
	v_pk_fma_f32 v[210:211], v[16:17], v[202:203], v[210:211]
	v_pk_fma_f32 v[208:209], v[2:3], v[204:205], v[208:209]
	v_pk_fma_f32 v[210:211], v[6:7], v[204:205], v[210:211]
	v_pk_fma_f32 v[208:209], v[4:5], v[206:207], v[208:209]
	v_pk_fma_f32 v[210:211], v[8:9], v[206:207], v[210:211]
	v_add_f32_e32 v160, v208, v209
	v_add_f32_e32 v161, v210, v211
	ds_read_b128 v[192:195], v44 offset:45056
	ds_read_b128 v[196:199], v44 offset:46080
	ds_read_b128 v[200:203], v44 offset:47104
	ds_read_b128 v[204:207], v44 offset:48128
	s_waitcnt lgkmcnt(4)
	v_pk_mul_f32 v[208:209], v[26:27], v[176:177]
	v_pk_mul_f32 v[210:211], v[30:31], v[176:177]
	v_pk_fma_f32 v[208:209], v[28:29], v[178:179], v[208:209]
	v_pk_fma_f32 v[210:211], v[32:33], v[178:179], v[210:211]
	v_pk_fma_f32 v[208:209], v[22:23], v[180:181], v[208:209]
	v_pk_fma_f32 v[210:211], v[18:19], v[180:181], v[210:211]
	v_pk_fma_f32 v[208:209], v[24:25], v[182:183], v[208:209]
	v_pk_fma_f32 v[210:211], v[20:21], v[182:183], v[210:211]
	v_pk_fma_f32 v[208:209], v[10:11], v[184:185], v[208:209]
	v_pk_fma_f32 v[210:211], v[14:15], v[184:185], v[210:211]
	v_pk_fma_f32 v[208:209], v[12:13], v[186:187], v[208:209]
	v_pk_fma_f32 v[210:211], v[16:17], v[186:187], v[210:211]
	v_pk_fma_f32 v[208:209], v[2:3], v[188:189], v[208:209]
	v_pk_fma_f32 v[210:211], v[6:7], v[188:189], v[210:211]
	v_pk_fma_f32 v[208:209], v[4:5], v[190:191], v[208:209]
	v_pk_fma_f32 v[210:211], v[8:9], v[190:191], v[210:211]
	v_add_f32_e32 v162, v208, v209
	v_add_f32_e32 v163, v210, v211
	ds_read_b128 v[176:179], v44 offset:49152
	ds_read_b128 v[180:183], v44 offset:50176
	ds_read_b128 v[184:187], v44 offset:51200
	ds_read_b128 v[188:191], v44 offset:52224
	s_waitcnt lgkmcnt(4)
	v_pk_mul_f32 v[208:209], v[26:27], v[192:193]
	v_pk_mul_f32 v[210:211], v[30:31], v[192:193]
	v_pk_fma_f32 v[208:209], v[28:29], v[194:195], v[208:209]
	v_pk_fma_f32 v[210:211], v[32:33], v[194:195], v[210:211]
	v_pk_fma_f32 v[208:209], v[22:23], v[196:197], v[208:209]
	v_pk_fma_f32 v[210:211], v[18:19], v[196:197], v[210:211]
	v_pk_fma_f32 v[208:209], v[24:25], v[198:199], v[208:209]
	v_pk_fma_f32 v[210:211], v[20:21], v[198:199], v[210:211]
	v_pk_fma_f32 v[208:209], v[10:11], v[200:201], v[208:209]
	v_pk_fma_f32 v[210:211], v[14:15], v[200:201], v[210:211]
	v_pk_fma_f32 v[208:209], v[12:13], v[202:203], v[208:209]
	v_pk_fma_f32 v[210:211], v[16:17], v[202:203], v[210:211]
	v_pk_fma_f32 v[208:209], v[2:3], v[204:205], v[208:209]
	v_pk_fma_f32 v[210:211], v[6:7], v[204:205], v[210:211]
	v_pk_fma_f32 v[208:209], v[4:5], v[206:207], v[208:209]
	v_pk_fma_f32 v[210:211], v[8:9], v[206:207], v[210:211]
	v_add_f32_e32 v164, v208, v209
	v_add_f32_e32 v165, v210, v211
	ds_read_b128 v[192:195], v44 offset:53248
	ds_read_b128 v[196:199], v44 offset:54272
	ds_read_b128 v[200:203], v44 offset:55296
	ds_read_b128 v[204:207], v44 offset:56320
	s_waitcnt lgkmcnt(4)
	v_pk_mul_f32 v[208:209], v[26:27], v[176:177]
	v_pk_mul_f32 v[210:211], v[30:31], v[176:177]
	v_pk_fma_f32 v[208:209], v[28:29], v[178:179], v[208:209]
	v_pk_fma_f32 v[210:211], v[32:33], v[178:179], v[210:211]
	v_pk_fma_f32 v[208:209], v[22:23], v[180:181], v[208:209]
	v_pk_fma_f32 v[210:211], v[18:19], v[180:181], v[210:211]
	v_pk_fma_f32 v[208:209], v[24:25], v[182:183], v[208:209]
	v_pk_fma_f32 v[210:211], v[20:21], v[182:183], v[210:211]
	v_pk_fma_f32 v[208:209], v[10:11], v[184:185], v[208:209]
	v_pk_fma_f32 v[210:211], v[14:15], v[184:185], v[210:211]
	v_pk_fma_f32 v[208:209], v[12:13], v[186:187], v[208:209]
	v_pk_fma_f32 v[210:211], v[16:17], v[186:187], v[210:211]
	v_pk_fma_f32 v[208:209], v[2:3], v[188:189], v[208:209]
	v_pk_fma_f32 v[210:211], v[6:7], v[188:189], v[210:211]
	v_pk_fma_f32 v[208:209], v[4:5], v[190:191], v[208:209]
	v_pk_fma_f32 v[210:211], v[8:9], v[190:191], v[210:211]
	v_add_f32_e32 v166, v208, v209
	v_add_f32_e32 v167, v210, v211
	ds_read_b128 v[176:179], v44 offset:57344
	ds_read_b128 v[180:183], v44 offset:58368
	ds_read_b128 v[184:187], v44 offset:59392
	ds_read_b128 v[188:191], v44 offset:60416
	s_waitcnt lgkmcnt(4)
	v_pk_mul_f32 v[208:209], v[26:27], v[192:193]
	v_pk_mul_f32 v[210:211], v[30:31], v[192:193]
	v_pk_fma_f32 v[208:209], v[28:29], v[194:195], v[208:209]
	v_pk_fma_f32 v[210:211], v[32:33], v[194:195], v[210:211]
	v_pk_fma_f32 v[208:209], v[22:23], v[196:197], v[208:209]
	v_pk_fma_f32 v[210:211], v[18:19], v[196:197], v[210:211]
	v_pk_fma_f32 v[208:209], v[24:25], v[198:199], v[208:209]
	v_pk_fma_f32 v[210:211], v[20:21], v[198:199], v[210:211]
	v_pk_fma_f32 v[208:209], v[10:11], v[200:201], v[208:209]
	v_pk_fma_f32 v[210:211], v[14:15], v[200:201], v[210:211]
	v_pk_fma_f32 v[208:209], v[12:13], v[202:203], v[208:209]
	v_pk_fma_f32 v[210:211], v[16:17], v[202:203], v[210:211]
	v_pk_fma_f32 v[208:209], v[2:3], v[204:205], v[208:209]
	v_pk_fma_f32 v[210:211], v[6:7], v[204:205], v[210:211]
	v_pk_fma_f32 v[208:209], v[4:5], v[206:207], v[208:209]
	v_pk_fma_f32 v[210:211], v[8:9], v[206:207], v[210:211]
	v_add_f32_e32 v168, v208, v209
	v_add_f32_e32 v169, v210, v211
	ds_read_b128 v[192:195], v44 offset:61440
	ds_read_b128 v[196:199], v44 offset:62464
	ds_read_b128 v[200:203], v44 offset:63488
	ds_read_b128 v[204:207], v44 offset:64512
	s_waitcnt lgkmcnt(4)
	v_pk_mul_f32 v[208:209], v[26:27], v[176:177]
	v_pk_mul_f32 v[210:211], v[30:31], v[176:177]
	v_pk_fma_f32 v[208:209], v[28:29], v[178:179], v[208:209]
	v_pk_fma_f32 v[210:211], v[32:33], v[178:179], v[210:211]
	v_pk_fma_f32 v[208:209], v[22:23], v[180:181], v[208:209]
	v_pk_fma_f32 v[210:211], v[18:19], v[180:181], v[210:211]
	v_pk_fma_f32 v[208:209], v[24:25], v[182:183], v[208:209]
	v_pk_fma_f32 v[210:211], v[20:21], v[182:183], v[210:211]
	v_pk_fma_f32 v[208:209], v[10:11], v[184:185], v[208:209]
	v_pk_fma_f32 v[210:211], v[14:15], v[184:185], v[210:211]
	v_pk_fma_f32 v[208:209], v[12:13], v[186:187], v[208:209]
	v_pk_fma_f32 v[210:211], v[16:17], v[186:187], v[210:211]
	v_pk_fma_f32 v[208:209], v[2:3], v[188:189], v[208:209]
	v_pk_fma_f32 v[210:211], v[6:7], v[188:189], v[210:211]
	v_pk_fma_f32 v[208:209], v[4:5], v[190:191], v[208:209]
	v_pk_fma_f32 v[210:211], v[8:9], v[190:191], v[210:211]
	v_add_f32_e32 v170, v208, v209
	v_add_f32_e32 v171, v210, v211
	s_waitcnt lgkmcnt(0)
	v_pk_mul_f32 v[208:209], v[26:27], v[192:193]
	v_pk_mul_f32 v[210:211], v[30:31], v[192:193]
	v_pk_fma_f32 v[208:209], v[28:29], v[194:195], v[208:209]
	v_pk_fma_f32 v[210:211], v[32:33], v[194:195], v[210:211]
	v_pk_fma_f32 v[208:209], v[22:23], v[196:197], v[208:209]
	v_pk_fma_f32 v[210:211], v[18:19], v[196:197], v[210:211]
	v_pk_fma_f32 v[208:209], v[24:25], v[198:199], v[208:209]
	v_pk_fma_f32 v[210:211], v[20:21], v[198:199], v[210:211]
	v_pk_fma_f32 v[208:209], v[10:11], v[200:201], v[208:209]
	v_pk_fma_f32 v[210:211], v[14:15], v[200:201], v[210:211]
	v_pk_fma_f32 v[208:209], v[12:13], v[202:203], v[208:209]
	v_pk_fma_f32 v[210:211], v[16:17], v[202:203], v[210:211]
	v_pk_fma_f32 v[208:209], v[2:3], v[204:205], v[208:209]
	v_pk_fma_f32 v[210:211], v[6:7], v[204:205], v[210:211]
	v_pk_fma_f32 v[208:209], v[4:5], v[206:207], v[208:209]
	v_pk_fma_f32 v[210:211], v[8:9], v[206:207], v[210:211]
	v_add_f32_e32 v172, v208, v209
	v_add_f32_e32 v173, v210, v211
	v_cndmask_b32_e32 v4, v142, v158, vcc
	ds_bpermute_b32 v4, v46, v4
	v_cndmask_b32_e32 v6, v144, v160, vcc
	ds_bpermute_b32 v6, v46, v6
	v_cndmask_b32_e32 v7, v146, v162, vcc
	ds_bpermute_b32 v7, v46, v7
	v_cndmask_b32_e32 v5, v158, v142, vcc
	s_waitcnt lgkmcnt(2)
	v_add_f32_e32 v4, v5, v4
	v_cndmask_b32_e32 v5, v160, v144, vcc
	s_waitcnt lgkmcnt(1)
	v_add_f32_e32 v5, v5, v6
	v_cndmask_b32_e32 v6, v162, v146, vcc
	s_waitcnt lgkmcnt(0)
	v_add_f32_e32 v6, v6, v7
	v_cndmask_b32_e32 v7, v148, v164, vcc
	ds_bpermute_b32 v7, v46, v7
	v_cndmask_b32_e32 v9, v150, v166, vcc
	ds_bpermute_b32 v9, v46, v9
	v_cndmask_b32_e32 v10, v152, v168, vcc
	ds_bpermute_b32 v10, v46, v10
	v_cndmask_b32_e32 v8, v164, v148, vcc
	s_waitcnt lgkmcnt(2)
	v_add_f32_e32 v7, v8, v7
	v_cndmask_b32_e32 v8, v166, v150, vcc
	s_waitcnt lgkmcnt(1)
	v_add_f32_e32 v8, v8, v9
	v_cndmask_b32_e32 v9, v168, v152, vcc
	v_cndmask_b32_e32 v13, v156, v172, vcc
	s_waitcnt lgkmcnt(0)
	v_add_f32_e32 v9, v9, v10
	v_cndmask_b32_e32 v10, v154, v170, vcc
	ds_bpermute_b32 v13, v46, v13
	ds_bpermute_b32 v10, v46, v10
	v_cndmask_b32_e32 v2, v172, v156, vcc
	v_cndmask_b32_e32 v12, v170, v154, vcc
	s_waitcnt lgkmcnt(1)
	v_add_f32_e32 v2, v2, v13
	v_cndmask_b32_e64 v14, v4, v8, s[0:1]
	s_waitcnt lgkmcnt(0)
	v_add_f32_e32 v10, v12, v10
	v_cndmask_b32_e64 v4, v8, v4, s[0:1]
	v_cndmask_b32_e64 v8, v5, v9, s[0:1]
	v_cndmask_b32_e64 v12, v7, v2, s[0:1]
	ds_bpermute_b32 v8, v47, v8
	ds_bpermute_b32 v12, v47, v12
	v_cndmask_b32_e64 v5, v9, v5, s[0:1]
	v_cndmask_b32_e64 v9, v6, v10, s[0:1]
	ds_bpermute_b32 v14, v47, v14
	ds_bpermute_b32 v9, v47, v9
	v_cndmask_b32_e64 v2, v2, v7, s[0:1]
	s_waitcnt lgkmcnt(3)
	v_add_f32_e32 v5, v5, v8
	s_waitcnt lgkmcnt(2)
	v_add_f32_e32 v2, v2, v12
	v_cndmask_b32_e64 v8, v5, v2, s[8:9]
	ds_bpermute_b32 v8, v48, v8
	v_cndmask_b32_e64 v6, v10, v6, s[0:1]
	s_waitcnt lgkmcnt(2)
	v_add_f32_e32 v4, v4, v14
	s_waitcnt lgkmcnt(1)
	v_add_f32_e32 v6, v6, v9
	v_cndmask_b32_e64 v7, v4, v6, s[8:9]
	ds_bpermute_b32 v7, v48, v7
	v_cndmask_b32_e64 v4, v6, v4, s[8:9]
	v_cndmask_b32_e64 v2, v2, v5, s[8:9]
	v_cndmask_b32_e32 v6, v143, v159, vcc
	s_waitcnt lgkmcnt(1)
	v_add_f32_e32 v2, v2, v8
	ds_bpermute_b32 v6, v46, v6
	v_cndmask_b32_e32 v8, v145, v161, vcc
	ds_bpermute_b32 v8, v46, v8
	v_cndmask_b32_e32 v9, v147, v163, vcc
	ds_bpermute_b32 v9, v46, v9
	s_waitcnt lgkmcnt(3)
	v_add_f32_e32 v4, v4, v7
	v_cndmask_b32_e32 v7, v159, v143, vcc
	s_waitcnt lgkmcnt(2)
	v_add_f32_e32 v6, v7, v6
	v_cndmask_b32_e32 v7, v161, v145, vcc
	s_waitcnt lgkmcnt(1)
	v_add_f32_e32 v7, v7, v8
	v_cndmask_b32_e32 v8, v163, v147, vcc
	s_waitcnt lgkmcnt(0)
	v_add_f32_e32 v8, v8, v9
	v_cndmask_b32_e32 v9, v149, v165, vcc
	ds_bpermute_b32 v9, v46, v9
	v_cndmask_b32_e32 v11, v151, v167, vcc
	ds_bpermute_b32 v11, v46, v11
	v_cndmask_b32_e32 v12, v153, v169, vcc
	ds_bpermute_b32 v12, v46, v12
	v_cndmask_b32_e32 v10, v165, v149, vcc
	s_waitcnt lgkmcnt(2)
	v_add_f32_e32 v9, v10, v9
	v_cndmask_b32_e32 v10, v167, v151, vcc
	s_waitcnt lgkmcnt(1)
	v_add_f32_e32 v10, v10, v11
	v_cndmask_b32_e32 v11, v169, v153, vcc
	s_waitcnt lgkmcnt(0)
	v_add_f32_e32 v11, v11, v12
	v_cndmask_b32_e32 v12, v155, v171, vcc
	v_cndmask_b32_e32 v14, v157, v173, vcc
	ds_bpermute_b32 v12, v46, v12
	ds_bpermute_b32 v14, v46, v14
	v_cndmask_b32_e32 v13, v171, v155, vcc
	v_cndmask_b32_e32 v3, v173, v157, vcc
	v_cndmask_b32_e64 v15, v6, v10, s[0:1]
	s_waitcnt lgkmcnt(1)
	v_add_f32_e32 v12, v13, v12
	s_waitcnt lgkmcnt(0)
	v_add_f32_e32 v3, v3, v14
	v_cndmask_b32_e64 v6, v10, v6, s[0:1]
	v_cndmask_b32_e64 v10, v7, v11, s[0:1]
	v_cndmask_b32_e64 v7, v11, v7, s[0:1]
	v_cndmask_b32_e64 v11, v8, v12, s[0:1]
	v_cndmask_b32_e64 v13, v9, v3, s[0:1]
	ds_bpermute_b32 v15, v47, v15
	ds_bpermute_b32 v10, v47, v10
	ds_bpermute_b32 v11, v47, v11
	ds_bpermute_b32 v13, v47, v13
	v_cndmask_b32_e64 v8, v12, v8, s[0:1]
	v_cndmask_b32_e64 v3, v3, v9, s[0:1]
	s_waitcnt lgkmcnt(3)
	v_add_f32_e32 v6, v6, v15
	s_waitcnt lgkmcnt(2)
	v_add_f32_e32 v7, v7, v10
	s_waitcnt lgkmcnt(1)
	v_add_f32_e32 v8, v8, v11
	s_waitcnt lgkmcnt(0)
	v_add_f32_e32 v3, v3, v13
	v_cndmask_b32_e64 v9, v6, v8, s[8:9]
	v_cndmask_b32_e64 v10, v7, v3, s[8:9]
	ds_bpermute_b32 v9, v48, v9
	ds_bpermute_b32 v10, v48, v10
	v_cndmask_b32_e64 v6, v8, v6, s[8:9]
	v_cndmask_b32_e64 v3, v3, v7, s[8:9]
	v_cndmask_b32_e64 v5, v4, v2, s[4:5]
	s_waitcnt lgkmcnt(1)
	v_add_f32_e32 v6, v6, v9
	s_waitcnt lgkmcnt(0)
	v_add_f32_e32 v3, v3, v10
	v_cndmask_b32_e64 v7, v6, v3, s[4:5]
	ds_bpermute_b32 v5, v49, v5
	ds_bpermute_b32 v7, v49, v7
	v_cndmask_b32_e64 v2, v2, v4, s[4:5]
	v_cndmask_b32_e64 v3, v3, v6, s[4:5]
	s_waitcnt lgkmcnt(1)
	v_add_f32_e32 v2, v2, v5
	s_waitcnt lgkmcnt(0)
	v_add_f32_e32 v3, v3, v7
	ds_bpermute_b32 v4, v50, v2
	ds_bpermute_b32 v6, v50, v3
	s_waitcnt lgkmcnt(1)
	v_add_f32_e32 v4, v2, v4
	s_waitcnt lgkmcnt(0)
	v_add_f32_e32 v2, v3, v6
	ds_bpermute_b32 v5, v51, v4
	ds_bpermute_b32 v3, v51, v2
	s_and_saveexec_b64 s[18:19], s[6:7]
	s_cbranch_execz .LBB0_37
	s_waitcnt lgkmcnt(1)
	v_add_f32_e32 v4, v4, v5
	v_add_f32_e32 v4, v1, v4
	v_mul_f32_e64 v5, |v4|, s20
	v_exp_f32_e32 v5, v5
	s_waitcnt lgkmcnt(0)
	v_add_f32_e32 v2, v2, v3
	v_add_f32_e32 v6, v1, v2
	v_max_f32_e32 v4, 0, v4
	v_add_f32_e32 v7, 1.0, v5
	v_add_f32_e32 v2, -1.0, v7
	v_sub_f32_e32 v3, v2, v7
	v_add_f32_e32 v3, 1.0, v3
	v_sub_f32_e32 v2, v5, v2
	v_add_f32_e32 v8, v2, v3
	v_frexp_mant_f32_e32 v9, v7
	v_cvt_f64_f32_e32 v[2:3], v7
	v_frexp_exp_i32_f64_e32 v2, v[2:3]
	v_cmp_gt_f32_e64 s[10:11], s21, v9
	s_nop 1
	v_subbrev_co_u32_e64 v2, s[10:11], 0, v2, s[10:11]
	v_sub_u32_e32 v3, 0, v2
	v_ldexp_f32 v7, v7, v3
	v_ldexp_f32 v3, v8, v3
	v_add_f32_e32 v8, -1.0, v7
	v_add_f32_e32 v11, 1.0, v7
	v_add_f32_e32 v9, 1.0, v8
	v_add_f32_e32 v12, -1.0, v11
	v_sub_f32_e32 v9, v7, v9
	v_sub_f32_e32 v7, v7, v12
	v_add_f32_e32 v9, v3, v9
	v_add_f32_e32 v3, v3, v7
	v_add_f32_e32 v7, v11, v3
	v_rcp_f32_e32 v12, v7
	v_add_f32_e32 v10, v8, v9
	v_sub_f32_e32 v8, v10, v8
	v_sub_f32_e32 v8, v9, v8
	v_sub_f32_e32 v9, v7, v11
	v_sub_f32_e32 v3, v3, v9
	v_mul_f32_e32 v9, v10, v12
	v_mul_f32_e32 v11, v7, v9
	v_fma_f32 v13, v9, v7, -v11
	v_fmac_f32_e32 v13, v9, v3
	v_add_f32_e32 v14, v11, v13
	v_sub_f32_e32 v15, v10, v14
	v_sub_f32_e32 v10, v10, v15
	v_sub_f32_e32 v11, v14, v11
	v_sub_f32_e32 v10, v10, v14
	v_add_f32_e32 v8, v8, v10
	v_sub_f32_e32 v10, v11, v13
	v_add_f32_e32 v8, v10, v8
	v_add_f32_e32 v10, v15, v8
	v_mul_f32_e32 v11, v12, v10
	v_mul_f32_e32 v13, v7, v11
	v_fma_f32 v7, v11, v7, -v13
	v_fmac_f32_e32 v7, v11, v3
	v_sub_f32_e32 v3, v15, v10
	v_add_f32_e32 v3, v8, v3
	v_add_f32_e32 v8, v13, v7
	v_sub_f32_e32 v14, v10, v8
	v_sub_f32_e32 v10, v10, v14
	v_sub_f32_e32 v13, v8, v13
	v_sub_f32_e32 v8, v10, v8
	v_add_f32_e32 v3, v3, v8
	v_sub_f32_e32 v7, v13, v7
	v_cvt_f32_i32_e32 v2, v2
	v_add_f32_e32 v3, v7, v3
	v_add_f32_e32 v7, v9, v11
	v_add_f32_e32 v3, v14, v3
	v_sub_f32_e32 v8, v7, v9
	v_mul_f32_e32 v3, v12, v3
	v_sub_f32_e32 v8, v11, v8
	v_add_f32_e32 v3, v8, v3
	v_mul_f32_e32 v11, 0x3f317218, v2
	v_add_f32_e32 v8, v7, v3
	v_fma_f32 v12, v2, s22, -v11
	v_mul_f32_e32 v9, v8, v8
	v_fmac_f32_e32 v12, 0xb102e308, v2
	v_sub_f32_e32 v2, v8, v7
	v_fmamk_f32 v10, v9, 0x3e9b6dac, v52
	v_sub_f32_e32 v2, v3, v2
	v_add_f32_e32 v3, v11, v12
	v_fmaak_f32 v10, v9, v10, 0x3f2aaada
	v_sub_f32_e32 v7, v3, v11
	v_ldexp_f32 v11, v8, 1
	v_mul_f32_e32 v8, v8, v9
	v_mul_f32_e32 v8, v8, v10
	v_add_f32_e32 v9, v11, v8
	v_sub_f32_e32 v10, v9, v11
	v_ldexp_f32 v2, v2, 1
	v_sub_f32_e32 v8, v8, v10
	v_add_f32_e32 v2, v2, v8
	v_add_f32_e32 v8, v9, v2
	v_sub_f32_e32 v9, v8, v9
	v_sub_f32_e32 v2, v2, v9
	v_add_f32_e32 v9, v3, v8
	v_sub_f32_e32 v10, v9, v3
	v_sub_f32_e32 v11, v9, v10
	v_sub_f32_e32 v7, v12, v7
	v_sub_f32_e32 v3, v3, v11
	v_sub_f32_e32 v8, v8, v10
	v_add_f32_e32 v3, v8, v3
	v_add_f32_e32 v8, v7, v2
	v_sub_f32_e32 v10, v8, v7
	v_sub_f32_e32 v11, v8, v10
	v_sub_f32_e32 v7, v7, v11
	v_sub_f32_e32 v2, v2, v10
	v_add_f32_e32 v3, v8, v3
	v_add_f32_e32 v2, v2, v7
	v_add_f32_e32 v7, v9, v3
	v_sub_f32_e32 v8, v7, v9
	v_sub_f32_e32 v3, v3, v8
	v_add_f32_e32 v2, v2, v3
	v_add_f32_e32 v2, v7, v2
	v_cmp_neq_f32_e64 s[10:11], s23, v5
	s_nop 1
	v_cndmask_b32_e64 v2, v53, v2, s[10:11]
	v_cmp_ngt_f32_e64 s[10:11], -1.0, v5
	s_nop 1
	v_cndmask_b32_e64 v2, v54, v2, s[10:11]
	v_cmp_neq_f32_e64 s[10:11], -1.0, v5
	s_nop 1
	v_cndmask_b32_e64 v2, v55, v2, s[10:11]
	v_cmp_lt_f32_e64 s[10:11], |v5|, s24
	s_nop 1
	v_cndmask_b32_e64 v2, v2, v5, s[10:11]
	v_add_f32_e32 v4, v4, v2
	v_mul_f32_e64 v2, |v6|, s20
	v_exp_f32_e32 v5, v2
	s_lshl_b64 s[10:11], s[16:17], 6
	v_lshl_add_u64 v[2:3], v[38:39], 0, s[10:11]
	global_store_dword v[2:3], v4, off
	v_max_f32_e32 v4, 0, v6
	v_add_f32_e32 v6, 1.0, v5
	v_add_f32_e32 v2, -1.0, v6
	v_sub_f32_e32 v3, v2, v6
	v_add_f32_e32 v3, 1.0, v3
	v_sub_f32_e32 v2, v5, v2
	v_add_f32_e32 v7, v2, v3
	v_frexp_mant_f32_e32 v8, v6
	v_cvt_f64_f32_e32 v[2:3], v6
	v_frexp_exp_i32_f64_e32 v2, v[2:3]
	v_cmp_gt_f32_e64 s[10:11], s21, v8
	s_nop 1
	v_subbrev_co_u32_e64 v2, s[10:11], 0, v2, s[10:11]
	v_sub_u32_e32 v3, 0, v2
	v_ldexp_f32 v6, v6, v3
	v_ldexp_f32 v3, v7, v3
	v_add_f32_e32 v7, -1.0, v6
	v_add_f32_e32 v10, 1.0, v6
	v_add_f32_e32 v8, 1.0, v7
	v_add_f32_e32 v11, -1.0, v10
	v_sub_f32_e32 v8, v6, v8
	v_sub_f32_e32 v6, v6, v11
	v_add_f32_e32 v8, v3, v8
	v_add_f32_e32 v3, v3, v6
	v_add_f32_e32 v6, v10, v3
	v_rcp_f32_e32 v11, v6
	v_add_f32_e32 v9, v7, v8
	v_sub_f32_e32 v7, v9, v7
	v_sub_f32_e32 v7, v8, v7
	v_sub_f32_e32 v8, v6, v10
	v_sub_f32_e32 v3, v3, v8
	v_mul_f32_e32 v8, v9, v11
	v_mul_f32_e32 v10, v6, v8
	v_fma_f32 v12, v8, v6, -v10
	v_fmac_f32_e32 v12, v8, v3
	v_add_f32_e32 v13, v10, v12
	v_sub_f32_e32 v14, v9, v13
	v_sub_f32_e32 v9, v9, v14
	v_sub_f32_e32 v10, v13, v10
	v_sub_f32_e32 v9, v9, v13
	v_add_f32_e32 v7, v7, v9
	v_sub_f32_e32 v9, v10, v12
	v_add_f32_e32 v7, v9, v7
	v_add_f32_e32 v9, v14, v7
	v_mul_f32_e32 v10, v11, v9
	v_mul_f32_e32 v12, v6, v10
	v_fma_f32 v6, v10, v6, -v12
	v_fmac_f32_e32 v6, v10, v3
	v_sub_f32_e32 v3, v14, v9
	v_add_f32_e32 v3, v7, v3
	v_add_f32_e32 v7, v12, v6
	v_sub_f32_e32 v13, v9, v7
	v_sub_f32_e32 v9, v9, v13
	v_sub_f32_e32 v12, v7, v12
	v_sub_f32_e32 v7, v9, v7
	v_add_f32_e32 v3, v3, v7
	v_sub_f32_e32 v6, v12, v6
	v_cvt_f32_i32_e32 v2, v2
	v_add_f32_e32 v3, v6, v3
	v_add_f32_e32 v6, v8, v10
	v_add_f32_e32 v3, v13, v3
	v_sub_f32_e32 v7, v6, v8
	v_mul_f32_e32 v3, v11, v3
	v_sub_f32_e32 v7, v10, v7
	v_add_f32_e32 v3, v7, v3
	v_mul_f32_e32 v10, 0x3f317218, v2
	v_add_f32_e32 v7, v6, v3
	v_fma_f32 v11, v2, s22, -v10
	v_mul_f32_e32 v8, v7, v7
	v_fmac_f32_e32 v11, 0xb102e308, v2
	v_sub_f32_e32 v2, v7, v6
	v_fmamk_f32 v9, v8, 0x3e9b6dac, v52
	v_sub_f32_e32 v2, v3, v2
	v_add_f32_e32 v3, v10, v11
	v_fmaak_f32 v9, v8, v9, 0x3f2aaada
	v_sub_f32_e32 v6, v3, v10
	v_ldexp_f32 v10, v7, 1
	v_mul_f32_e32 v7, v7, v8
	v_mul_f32_e32 v7, v7, v9
	v_add_f32_e32 v8, v10, v7
	v_sub_f32_e32 v9, v8, v10
	v_ldexp_f32 v2, v2, 1
	v_sub_f32_e32 v7, v7, v9
	v_add_f32_e32 v2, v2, v7
	v_add_f32_e32 v7, v8, v2
	v_sub_f32_e32 v8, v7, v8
	v_sub_f32_e32 v2, v2, v8
	v_add_f32_e32 v8, v3, v7
	v_sub_f32_e32 v9, v8, v3
	v_sub_f32_e32 v10, v8, v9
	v_sub_f32_e32 v6, v11, v6
	v_sub_f32_e32 v3, v3, v10
	v_sub_f32_e32 v7, v7, v9
	v_add_f32_e32 v3, v7, v3
	v_add_f32_e32 v7, v6, v2
	v_sub_f32_e32 v9, v7, v6
	v_sub_f32_e32 v10, v7, v9
	v_sub_f32_e32 v6, v6, v10
	v_sub_f32_e32 v2, v2, v9
	v_add_f32_e32 v3, v7, v3
	v_add_f32_e32 v2, v2, v6
	v_add_f32_e32 v6, v8, v3
	v_sub_f32_e32 v7, v6, v8
	v_sub_f32_e32 v3, v3, v7
	v_add_f32_e32 v2, v2, v3
	v_add_f32_e32 v2, v6, v2
	v_cmp_neq_f32_e64 s[10:11], s23, v5
	s_nop 1
	v_cndmask_b32_e64 v2, v53, v2, s[10:11]
	v_cmp_ngt_f32_e64 s[10:11], -1.0, v5
	s_nop 1
	v_cndmask_b32_e64 v2, v54, v2, s[10:11]
	v_cmp_neq_f32_e64 s[10:11], -1.0, v5
	s_nop 1
	v_cndmask_b32_e64 v2, v55, v2, s[10:11]
	v_cmp_lt_f32_e64 s[10:11], |v5|, s24
	s_nop 1
	v_cndmask_b32_e64 v2, v2, v5, s[10:11]
	s_lshl_b64 s[10:11], s[14:15], 6
	v_add_f32_e32 v4, v4, v2
	v_lshl_add_u64 v[2:3], v[38:39], 0, s[10:11]
	global_store_dword v[2:3], v4, off
	s_branch .LBB0_37
